# FFN-out residual epilogue: second half of the 16 residual loads issued only when the first load has returned (two bursts of 8)
# speedup vs baseline: 1.0105x; 1.0105x over previous
.LBB0_274:
	v_mbcnt_lo_u32_b32 v94, -1, 0
	v_mbcnt_hi_u32_b32 v94, -1, v94
	s_lshl_b32 s9, s25, 8
	v_ashrrev_i32_e32 v95, 1, v94
	s_lshl_b32 s7, s26, 8
	s_or_b32 s9, s9, s59
	v_and_b32_e32 v95, -8, v95
	s_add_i32 s7, s7, s58
	v_add_u32_e32 v204, s9, v95
	v_ashrrev_i32_e32 v205, 31, v204
	v_and_or_b32 v234, v94, 15, s7
	v_lshlrev_b64 v[236:237], 1, v[204:205]
	v_ashrrev_i32_e32 v235, 31, v234
	v_lshlrev_b32_e32 v244, 2, v94
	v_cmp_gt_u32_e32 vcc, 16, v94
	v_lshl_add_u64 v[94:95], s[42:43], 0, v[236:237]
	v_lshlrev_b64 v[238:239], 11, v[234:235]
	v_lshl_add_u64 v[96:97], v[94:95], 0, v[238:239]
	global_load_dwordx4 v[190:193], v[96:97], off
	global_load_dwordx4 v[186:189], v[96:97], off offset:256
	v_or_b32_e32 v230, 16, v234
	v_ashrrev_i32_e32 v231, 31, v230
	v_or_b32_e32 v210, 32, v234
	v_lshlrev_b64 v[232:233], 11, v[230:231]
	v_ashrrev_i32_e32 v211, 31, v210
	v_or_b32_e32 v226, 48, v234
	v_lshl_add_u64 v[96:97], v[94:95], 0, v[232:233]
	v_lshlrev_b64 v[212:213], 11, v[210:211]
	v_ashrrev_i32_e32 v227, 31, v226
	v_add_u32_e32 v222, 0x80, v234
	global_load_dwordx4 v[182:185], v[96:97], off
	global_load_dwordx4 v[178:181], v[96:97], off offset:256
	v_lshl_add_u64 v[96:97], v[94:95], 0, v[212:213]
	v_lshlrev_b64 v[228:229], 11, v[226:227]
	v_ashrrev_i32_e32 v223, 31, v222
	v_add_u32_e32 v218, 0x90, v234
	global_load_dwordx4 v[174:177], v[96:97], off
	global_load_dwordx4 v[170:173], v[96:97], off offset:256
	v_lshl_add_u64 v[96:97], v[94:95], 0, v[228:229]
	v_lshlrev_b64 v[224:225], 11, v[222:223]
	v_ashrrev_i32_e32 v219, 31, v218
	v_add_u32_e32 v214, 0xa0, v234
	v_add_u32_e32 v206, 0xb0, v234
	global_load_dwordx4 v[166:169], v[96:97], off
	global_load_dwordx4 v[162:165], v[96:97], off offset:256
	v_lshlrev_b64 v[220:221], 11, v[218:219]
	v_ashrrev_i32_e32 v215, 31, v214
	v_ashrrev_i32_e32 v207, 31, v206
	v_lshlrev_b64 v[216:217], 11, v[214:215]
	v_lshlrev_b64 v[208:209], 11, v[206:207]
	v_xor_b32_e32 v245, 64, v244
	v_xor_b32_e32 v244, 0x80, v244
	s_lshl_b32 s82, s25, 2
	s_ashr_i32 s83, s82, 31
	s_waitcnt vmcnt(7)
	v_lshl_add_u64 v[96:97], v[94:95], 0, v[224:225]
	global_load_dwordx4 v[158:161], v[96:97], off
	global_load_dwordx4 v[150:153], v[96:97], off offset:256
	v_lshl_add_u64 v[96:97], v[94:95], 0, v[220:221]
	global_load_dwordx4 v[142:145], v[96:97], off
	global_load_dwordx4 v[138:141], v[96:97], off offset:256
	v_lshl_add_u64 v[96:97], v[94:95], 0, v[216:217]
	v_lshl_add_u64 v[94:95], v[94:95], 0, v[208:209]
	global_load_dwordx4 v[126:129], v[96:97], off
	global_load_dwordx4 v[114:117], v[96:97], off offset:256
	global_load_dwordx4 v[106:109], v[94:95], off
	s_nop 0
	global_load_dwordx4 v[94:97], v[94:95], off offset:256
	v_lshlrev_b32_e32 v246, 16, v190
	v_and_b32_e32 v247, 0xffff0000, v190
	v_lshlrev_b32_e32 v190, 16, v191
	v_and_b32_e32 v191, 0xffff0000, v191
	v_pk_fma_f32 v[156:157], v[156:157], 0.5, v[190:191] op_sel_hi:[1,0,1]
	v_lshlrev_b32_e32 v190, 16, v192
	v_and_b32_e32 v191, 0xffff0000, v192
	v_pk_fma_f32 v[146:147], v[146:147], 0.5, v[190:191] op_sel_hi:[1,0,1]
	v_pk_fma_f32 v[154:155], v[154:155], 0.5, v[246:247] op_sel_hi:[1,0,1]
	v_pk_add_f32 v[190:191], v[146:147], 0 op_sel_hi:[1,0]
	v_lshlrev_b32_e32 v146, 16, v193
	v_and_b32_e32 v147, 0xffff0000, v193
	v_pk_add_f32 v[154:155], v[154:155], 0 op_sel_hi:[1,0]
	v_pk_fma_f32 v[146:147], v[148:149], 0.5, v[146:147] op_sel_hi:[1,0,1]
	v_pk_add_f32 v[156:157], v[156:157], 0 op_sel_hi:[1,0]
	v_pk_add_f32 v[192:193], v[146:147], 0 op_sel_hi:[1,0]
	v_cvt_pk_bf16_f32 v146, v154, v155
	v_lshl_add_u64 v[154:155], s[88:89], 0, v[238:239]
	v_cvt_pk_bf16_f32 v147, v156, v157
	v_cvt_pk_bf16_f32 v148, v190, v191
	v_cvt_pk_bf16_f32 v149, v192, v193
	v_lshl_add_u64 v[154:155], v[154:155], 0, v[236:237]
	global_store_dwordx4 v[154:155], v[146:149], off
	v_lshlrev_b32_e32 v156, 16, v146
	v_lshlrev_b32_e32 v157, 16, v147
	v_and_b32_e32 v146, 0xffff0000, v146
	v_and_b32_e32 v147, 0xffff0000, v147
	v_mul_f32_e32 v146, v146, v146
	v_mul_f32_e32 v147, v147, v147
	v_lshlrev_b32_e32 v190, 16, v148
	v_and_b32_e32 v148, 0xffff0000, v148
	v_fmac_f32_e32 v146, v156, v156
	v_fmac_f32_e32 v147, v157, v157
	v_add_f32_e32 v146, v146, v147
	v_mul_f32_e32 v147, v148, v148
	v_lshlrev_b32_e32 v191, 16, v149
	v_and_b32_e32 v149, 0xffff0000, v149
	v_fmac_f32_e32 v147, v190, v190
	v_add_f32_e32 v146, v147, v146
	v_mul_f32_e32 v147, v149, v149
	v_fmac_f32_e32 v147, v191, v191
	v_add_f32_e32 v156, v147, v146
	s_waitcnt vmcnt(15)
	v_lshlrev_b32_e32 v146, 16, v186
	v_and_b32_e32 v147, 0xffff0000, v186
	v_pk_fma_f32 v[134:135], v[134:135], 0.5, v[146:147] op_sel_hi:[1,0,1]
	v_lshlrev_b32_e32 v146, 16, v187
	v_and_b32_e32 v147, 0xffff0000, v187
	v_pk_fma_f32 v[136:137], v[136:137], 0.5, v[146:147] op_sel_hi:[1,0,1]
	v_lshlrev_b32_e32 v146, 16, v188
	v_and_b32_e32 v147, 0xffff0000, v188
	v_pk_fma_f32 v[130:131], v[130:131], 0.5, v[146:147] op_sel_hi:[1,0,1]
	v_pk_add_f32 v[134:135], v[134:135], 0 op_sel_hi:[1,0]
	v_pk_add_f32 v[146:147], v[130:131], 0 op_sel_hi:[1,0]
	v_lshlrev_b32_e32 v130, 16, v189
	v_and_b32_e32 v131, 0xffff0000, v189
	v_pk_fma_f32 v[130:131], v[132:133], 0.5, v[130:131] op_sel_hi:[1,0,1]
	v_pk_add_f32 v[136:137], v[136:137], 0 op_sel_hi:[1,0]
	v_pk_add_f32 v[148:149], v[130:131], 0 op_sel_hi:[1,0]
	v_cvt_pk_bf16_f32 v130, v134, v135
	v_cvt_pk_bf16_f32 v131, v136, v137
	v_cvt_pk_bf16_f32 v132, v146, v147
	v_cvt_pk_bf16_f32 v133, v148, v149
	global_store_dwordx4 v[154:155], v[130:133], off offset:256
	v_lshlrev_b32_e32 v134, 16, v130
	v_lshlrev_b32_e32 v135, 16, v131
	v_and_b32_e32 v130, 0xffff0000, v130
	v_and_b32_e32 v131, 0xffff0000, v131
	v_mul_f32_e32 v130, v130, v130
	v_fmac_f32_e32 v130, v134, v134
	v_mul_f32_e32 v131, v131, v131
	v_lshlrev_b32_e32 v136, 16, v132
	v_and_b32_e32 v132, 0xffff0000, v132
	v_add_f32_e32 v130, v130, v156
	v_fmac_f32_e32 v131, v135, v135
	v_add_f32_e32 v130, v131, v130
	v_mul_f32_e32 v131, v132, v132
	v_lshlrev_b32_e32 v137, 16, v133
	v_and_b32_e32 v133, 0xffff0000, v133
	v_fmac_f32_e32 v131, v136, v136
	v_add_f32_e32 v130, v131, v130
	v_mul_f32_e32 v131, v133, v133
	v_fmac_f32_e32 v131, v137, v137
	v_add_f32_e32 v130, v131, v130
	ds_bpermute_b32 v131, v245, v130
	s_waitcnt lgkmcnt(0)
	v_add_f32_e32 v130, v130, v131
	ds_bpermute_b32 v131, v244, v130
	s_and_saveexec_b64 s[48:49], vcc
	s_mov_b32 s31, 0xf800000
	s_cbranch_execz .LBB0_276
	v_lshlrev_b64 v[132:133], 6, v[234:235]
	v_lshl_add_u64 v[132:133], s[38:39], 0, v[132:133]
	v_lshl_add_u64 v[132:133], s[82:83], 2, v[132:133]
	s_lshl_b32 s76, s55, 2
	v_lshl_add_u64 v[132:133], v[132:133], 0, s[76:77]
	s_waitcnt lgkmcnt(0)
	v_add_f32_e32 v130, v130, v131
	global_store_dword v[132:133], v130, off
